# adds: attention phase prefetches the 4 gate (az) loads before P.V instead of 4 dependent load-wait-store rounds
# speedup vs baseline: 1.0233x; 1.0025x over previous
; __device__ __forceinline__ f32x4 mfma16(bf16x8 a, bf16x8 b, f32x4 c) { return __builtin_amdgcn_mfma_f32_16x16x32_bf16(a, b, c, 0, 0, 0); }
; __device__ __forceinline__ void phase_attn(const Args& a, unsigned char* smem, int tid, int lane, int wave, bf16_t* Yout) {
;     ...
;             for (int c = 0; c < 8; ++c)
; #pragma unroll
;                 for (int hf = 0; hf < 2; ++hf) {
;                     const bf16_t* kp = Ks + (c * 32 + wo + 4 * hf) * 72 + 8 * g;
;                     const bf16x8 k0 = *(const bf16x8*)kp, k1 = *(const bf16x8*)(kp + 32);
;                     f32x4 s = {0.f, 0.f, 0.f, 0.f};
;                     s = mfma16(k0, qf0, s); s = mfma16(k1, qf1, s);
;                     st[16 + c * 2 + hf] = s * 0.125f;
;                 }
.LBB0_334:
	s_or_b64 exec, exec, s[22:23]
	ds_read_b128 v[8:11], v182
	ds_read_b128 v[12:15], v182 offset:64
	v_lshlrev_b32_e32 v114, 1, v114
	s_lshl_b32 s12, s12, 1
	s_add_i32 s53, s53, 2
	s_waitcnt lgkmcnt(1)
	v_mfma_f32_16x16x32_bf16 v[8:11], v[8:11], v[4:7], 0
	s_add_i32 s54, s54, -2
	s_add_i32 s66, s66, 8
	s_addk_i32 s55, 0x80
	s_waitcnt lgkmcnt(0)
	v_mfma_f32_16x16x32_bf16 v[8:11], v[12:15], v[0:3], v[8:11]
	s_cmpk_gt_u32 s66, 0x77
	s_nop 6
	v_pk_mul_f32 v[60:61], v[10:11], s[18:19] op_sel_hi:[1,0]
	v_pk_mul_f32 v[66:67], v[8:9], s[18:19] op_sel_hi:[1,0]
	ds_read_b128 v[8:11], v182 offset:576
	ds_read_b128 v[12:15], v182 offset:640
	s_waitcnt lgkmcnt(1)
	v_mfma_f32_16x16x32_bf16 v[8:11], v[8:11], v[4:7], 0
	s_waitcnt lgkmcnt(0)
	v_mfma_f32_16x16x32_bf16 v[8:11], v[12:15], v[0:3], v[8:11]
	s_nop 7
	v_pk_mul_f32 v[56:57], v[10:11], s[18:19] op_sel_hi:[1,0]
	v_pk_mul_f32 v[64:65], v[8:9], s[18:19] op_sel_hi:[1,0]
	ds_read_b128 v[8:11], v182 offset:4608
	ds_read_b128 v[12:15], v182 offset:4672
	s_waitcnt lgkmcnt(1)
	v_mfma_f32_16x16x32_bf16 v[8:11], v[8:11], v[4:7], 0
	s_waitcnt lgkmcnt(0)
	v_mfma_f32_16x16x32_bf16 v[8:11], v[12:15], v[0:3], v[8:11]
	s_nop 7
	v_pk_mul_f32 v[50:51], v[10:11], s[18:19] op_sel_hi:[1,0]
	v_pk_mul_f32 v[62:63], v[8:9], s[18:19] op_sel_hi:[1,0]
	ds_read_b128 v[8:11], v182 offset:5184
	ds_read_b128 v[12:15], v182 offset:5248
	s_waitcnt lgkmcnt(1)
	v_mfma_f32_16x16x32_bf16 v[8:11], v[8:11], v[4:7], 0
	s_waitcnt lgkmcnt(0)
	v_mfma_f32_16x16x32_bf16 v[8:11], v[12:15], v[0:3], v[8:11]
	s_nop 7
	v_pk_mul_f32 v[42:43], v[10:11], s[18:19] op_sel_hi:[1,0]
	v_pk_mul_f32 v[52:53], v[8:9], s[18:19] op_sel_hi:[1,0]
	ds_read_b128 v[8:11], v182 offset:9216
	ds_read_b128 v[12:15], v182 offset:9280
	s_waitcnt lgkmcnt(1)
	v_mfma_f32_16x16x32_bf16 v[8:11], v[8:11], v[4:7], 0
	s_waitcnt lgkmcnt(0)
	v_mfma_f32_16x16x32_bf16 v[8:11], v[12:15], v[0:3], v[8:11]
	s_nop 7
	v_pk_mul_f32 v[36:37], v[10:11], s[18:19] op_sel_hi:[1,0]
	v_pk_mul_f32 v[46:47], v[8:9], s[18:19] op_sel_hi:[1,0]
	ds_read_b128 v[8:11], v182 offset:9792
	ds_read_b128 v[12:15], v182 offset:9856
	s_waitcnt lgkmcnt(1)
	v_mfma_f32_16x16x32_bf16 v[8:11], v[8:11], v[4:7], 0
	s_waitcnt lgkmcnt(0)
	v_mfma_f32_16x16x32_bf16 v[8:11], v[12:15], v[0:3], v[8:11]
	s_nop 7
	v_pk_mul_f32 v[30:31], v[10:11], s[18:19] op_sel_hi:[1,0]
	v_pk_mul_f32 v[40:41], v[8:9], s[18:19] op_sel_hi:[1,0]
	ds_read_b128 v[8:11], v182 offset:13824
	ds_read_b128 v[12:15], v182 offset:13888
	s_waitcnt lgkmcnt(1)
	v_mfma_f32_16x16x32_bf16 v[8:11], v[8:11], v[4:7], 0
	s_waitcnt lgkmcnt(0)
	v_mfma_f32_16x16x32_bf16 v[8:11], v[12:15], v[0:3], v[8:11]
	s_nop 7
	v_pk_mul_f32 v[24:25], v[10:11], s[18:19] op_sel_hi:[1,0]
	v_pk_mul_f32 v[34:35], v[8:9], s[18:19] op_sel_hi:[1,0]
	ds_read_b128 v[8:11], v182 offset:14400
	ds_read_b128 v[12:15], v182 offset:14464
	s_waitcnt lgkmcnt(1)
	v_mfma_f32_16x16x32_bf16 v[8:11], v[8:11], v[4:7], 0
	s_waitcnt lgkmcnt(0)
	v_mfma_f32_16x16x32_bf16 v[8:11], v[12:15], v[0:3], v[8:11]
	s_nop 7
	v_pk_mul_f32 v[16:17], v[10:11], s[18:19] op_sel_hi:[1,0]
	v_pk_mul_f32 v[28:29], v[8:9], s[18:19] op_sel_hi:[1,0]
	ds_read_b128 v[8:11], v182 offset:18432
	ds_read_b128 v[12:15], v182 offset:18496
	s_waitcnt lgkmcnt(1)
	v_mfma_f32_16x16x32_bf16 v[8:11], v[8:11], v[4:7], 0
	s_waitcnt lgkmcnt(0)
	v_mfma_f32_16x16x32_bf16 v[8:11], v[12:15], v[0:3], v[8:11]
	s_nop 7
	v_pk_mul_f32 v[12:13], v[10:11], s[18:19] op_sel_hi:[1,0]
	v_pk_mul_f32 v[22:23], v[8:9], s[18:19] op_sel_hi:[1,0]
	ds_read_b128 v[8:11], v182 offset:19008
	ds_read_b128 v[18:21], v182 offset:19072
	s_waitcnt lgkmcnt(1)
	v_mfma_f32_16x16x32_bf16 v[8:11], v[8:11], v[4:7], 0
	s_waitcnt lgkmcnt(0)
	v_mfma_f32_16x16x32_bf16 v[18:21], v[18:21], v[0:3], v[8:11]
	s_nop 7
	v_pk_mul_f32 v[8:9], v[20:21], s[18:19] op_sel_hi:[1,0]
	v_pk_mul_f32 v[14:15], v[18:19], s[18:19] op_sel_hi:[1,0]
	ds_read_b128 v[18:21], v182 offset:23040
	ds_read_b128 v[184:187], v182 offset:23104
	s_waitcnt lgkmcnt(1)
	v_mfma_f32_16x16x32_bf16 v[18:21], v[18:21], v[4:7], 0
	s_waitcnt lgkmcnt(0)
	v_mfma_f32_16x16x32_bf16 v[18:21], v[184:187], v[0:3], v[18:21]
	ds_read_b128 v[184:187], v182 offset:23616
	ds_read_b128 v[188:191], v182 offset:23680
	s_waitcnt lgkmcnt(1)
	v_mfma_f32_16x16x32_bf16 v[184:187], v[184:187], v[4:7], 0
	s_nop 3
	v_mul_f32_e64 v10, v20, s18
	v_mul_f32_e64 v11, v21, s18
	v_pk_mul_f32 v[20:21], v[18:19], s[18:19] op_sel_hi:[1,0]
	s_waitcnt lgkmcnt(0)
	v_mfma_f32_16x16x32_bf16 v[184:187], v[188:191], v[0:3], v[184:187]
	s_nop 7
	v_pk_mul_f32 v[18:19], v[186:187], s[18:19] op_sel_hi:[1,0]
	v_pk_mul_f32 v[32:33], v[184:185], s[18:19] op_sel_hi:[1,0]
	ds_read_b128 v[184:187], v182 offset:27648
	ds_read_b128 v[188:191], v182 offset:27712
	s_waitcnt lgkmcnt(1)
	v_mfma_f32_16x16x32_bf16 v[184:187], v[184:187], v[4:7], 0
	s_waitcnt lgkmcnt(0)
	v_mfma_f32_16x16x32_bf16 v[184:187], v[188:191], v[0:3], v[184:187]
	s_nop 7
	v_pk_mul_f32 v[26:27], v[186:187], s[18:19] op_sel_hi:[1,0]
	v_pk_mul_f32 v[38:39], v[184:185], s[18:19] op_sel_hi:[1,0]
	ds_read_b128 v[184:187], v182 offset:28224
	ds_read_b128 v[188:191], v182 offset:28288
	s_waitcnt lgkmcnt(1)
	v_mfma_f32_16x16x32_bf16 v[184:187], v[184:187], v[4:7], 0
	s_waitcnt lgkmcnt(0)
	v_mfma_f32_16x16x32_bf16 v[184:187], v[188:191], v[0:3], v[184:187]
	s_nop 7
	v_pk_mul_f32 v[44:45], v[186:187], s[18:19] op_sel_hi:[1,0]
	v_pk_mul_f32 v[48:49], v[184:185], s[18:19] op_sel_hi:[1,0]
	ds_read_b128 v[184:187], v182 offset:32256
	ds_read_b128 v[188:191], v182 offset:32320
	s_waitcnt lgkmcnt(1)
	v_mfma_f32_16x16x32_bf16 v[184:187], v[184:187], v[4:7], 0
	s_waitcnt lgkmcnt(0)
; __device__ __forceinline__ void phase_attn(const Args& a, unsigned char* smem, int tid, int lane, int wave, bf16_t* Yout) {
;     ...
;                     st[16 + c * 2 + hf] = s * 0.125f;
;                 }
;             float mx = -1e30f;
; #pragma unroll
;             for (int t = 0; t < 32; ++t) mx = fmaxf(fmaxf(fmaxf(st[t][0], st[t][1]), fmaxf(st[t][2], st[t][3])), mx);
;             mx = fmaxf(mx, __shfl_xor(mx, 16)); mx = fmaxf(mx, __shfl_xor(mx, 32));
	v_mfma_f32_16x16x32_bf16 v[184:187], v[188:191], v[0:3], v[184:187]
	s_nop 7
	v_pk_mul_f32 v[54:55], v[186:187], s[18:19] op_sel_hi:[1,0]
	v_pk_mul_f32 v[58:59], v[184:185], s[18:19] op_sel_hi:[1,0]
	ds_read_b128 v[184:187], v182 offset:32832
	ds_read_b128 v[188:191], v182 offset:32896
	s_waitcnt lgkmcnt(1)
	v_mfma_f32_16x16x32_bf16 v[4:7], v[184:187], v[4:7], 0
	s_waitcnt lgkmcnt(0)
	v_mfma_f32_16x16x32_bf16 v[2:5], v[188:191], v[0:3], v[4:7]
	s_nop 5
	v_max_f32_e32 v6, v71, v71
	v_max_f32_e32 v7, v75, v75
	v_pk_mul_f32 v[0:1], v[4:5], s[18:19] op_sel_hi:[1,0]
	v_max_f32_e32 v4, v68, v68
	v_max_f32_e32 v5, v69, v69
	v_max_f32_e32 v4, v5, v4
	v_max_f32_e32 v5, v70, v70
	v_max_f32_e32 v5, v6, v5
	v_max3_f32 v4, v4, v5, s47
	v_max_f32_e32 v5, v72, v72
	v_max_f32_e32 v6, v73, v73
	v_max_f32_e32 v5, v6, v5
	v_max_f32_e32 v6, v74, v74
	v_max_f32_e32 v6, v7, v6
	v_max3_f32 v4, v5, v6, v4
	v_max_f32_e32 v5, v76, v76
	v_max_f32_e32 v6, v77, v77
	v_max_f32_e32 v5, v6, v5
	v_max_f32_e32 v6, v78, v78
	v_max_f32_e32 v7, v79, v79
	v_max_f32_e32 v6, v7, v6
	v_max3_f32 v4, v5, v6, v4
	v_max_f32_e32 v5, v80, v80
	v_max_f32_e32 v6, v81, v81
	v_max_f32_e32 v5, v6, v5
	v_max_f32_e32 v6, v82, v82
	v_max_f32_e32 v7, v83, v83
	v_max_f32_e32 v6, v7, v6
	v_max3_f32 v4, v5, v6, v4
	v_max_f32_e32 v5, v84, v84
	v_max_f32_e32 v6, v85, v85
	v_max_f32_e32 v5, v6, v5
	v_max_f32_e32 v6, v86, v86
	v_max_f32_e32 v7, v87, v87
	v_max_f32_e32 v6, v7, v6
	v_max3_f32 v4, v5, v6, v4
	v_max_f32_e32 v5, v88, v88
	v_max_f32_e32 v6, v89, v89
	v_max_f32_e32 v5, v6, v5
	v_max_f32_e32 v6, v90, v90
	v_max_f32_e32 v7, v91, v91
	v_max_f32_e32 v6, v7, v6
	v_max3_f32 v4, v5, v6, v4
	v_max_f32_e32 v5, v92, v92
	v_max_f32_e32 v6, v93, v93
	v_max_f32_e32 v5, v6, v5
	v_max_f32_e32 v6, v94, v94
	v_max_f32_e32 v7, v95, v95
	v_max_f32_e32 v6, v7, v6
	v_max3_f32 v4, v5, v6, v4
	v_max_f32_e32 v5, v96, v96
	v_max_f32_e32 v6, v97, v97
	v_max_f32_e32 v5, v6, v5
	v_max_f32_e32 v6, v98, v98
	v_max_f32_e32 v7, v99, v99
	v_max_f32_e32 v6, v7, v6
	v_max3_f32 v4, v5, v6, v4
	v_max_f32_e32 v5, v100, v100
	v_max_f32_e32 v6, v101, v101
	v_max_f32_e32 v5, v6, v5
	v_max_f32_e32 v6, v102, v102
	v_max_f32_e32 v7, v103, v103
	v_max_f32_e32 v6, v7, v6
	v_max3_f32 v4, v5, v6, v4
	v_max_f32_e32 v5, v104, v104
	v_max_f32_e32 v6, v105, v105
	v_max_f32_e32 v5, v6, v5
	v_max_f32_e32 v6, v106, v106
	v_max_f32_e32 v7, v107, v107
	v_max_f32_e32 v6, v7, v6
	v_max3_f32 v4, v5, v6, v4
	v_max_f32_e32 v5, v108, v108
	v_max_f32_e32 v6, v109, v109
	v_max_f32_e32 v5, v6, v5
	v_max_f32_e32 v6, v110, v110
	v_max_f32_e32 v7, v111, v111
	v_max_f32_e32 v6, v7, v6
	v_max3_f32 v4, v5, v6, v4
	v_max_f32_e32 v5, v147, v147
	v_max_f32_e32 v6, v148, v148
	v_max_f32_e32 v5, v6, v5
	v_max_f32_e32 v6, v149, v149
	v_max_f32_e32 v7, v150, v150
	v_max_f32_e32 v6, v7, v6
	v_max3_f32 v4, v5, v6, v4
	v_max_f32_e32 v5, v151, v151
	v_max_f32_e32 v6, v152, v152
	v_max_f32_e32 v5, v6, v5
	v_max_f32_e32 v6, v153, v153
	v_max_f32_e32 v7, v154, v154
	v_max_f32_e32 v6, v7, v6
	v_max3_f32 v4, v5, v6, v4
	v_max_f32_e32 v5, v155, v155
	v_max_f32_e32 v6, v216, v216
	v_max_f32_e32 v5, v6, v5
	v_max_f32_e32 v6, v217, v217
	v_max_f32_e32 v7, v218, v218
	v_max_f32_e32 v6, v7, v6
	v_max3_f32 v4, v5, v6, v4
	v_max_f32_e32 v5, v219, v219
	v_max_f32_e32 v6, v220, v220
	v_max_f32_e32 v5, v6, v5
	v_max_f32_e32 v6, v221, v221
	v_max_f32_e32 v7, v222, v222
	v_max_f32_e32 v6, v7, v6
	v_max3_f32 v4, v5, v6, v4
	v_max_f32_e32 v5, v223, v223
	v_max_f32_e32 v6, v224, v224
	v_max_f32_e32 v5, v6, v5
	v_max_f32_e32 v6, v225, v225
	v_max_f32_e32 v7, v226, v226
	v_max_f32_e32 v6, v7, v6
	v_max3_f32 v4, v5, v6, v4
	v_max_f32_e32 v5, v66, v67
	v_max_f32_e32 v6, v60, v61
	v_max3_f32 v4, v5, v6, v4
	v_max_f32_e32 v5, v64, v65
	v_max_f32_e32 v6, v56, v57
	v_max3_f32 v4, v5, v6, v4
	v_max_f32_e32 v5, v62, v63
	v_max_f32_e32 v6, v50, v51
	v_max3_f32 v4, v5, v6, v4
	v_max_f32_e32 v5, v52, v53
	v_max_f32_e32 v6, v42, v43
	v_max3_f32 v4, v5, v6, v4
	v_max_f32_e32 v5, v46, v47
	v_max_f32_e32 v6, v36, v37
	v_max3_f32 v4, v5, v6, v4
	v_max_f32_e32 v5, v40, v41
	v_max_f32_e32 v6, v30, v31
	v_max3_f32 v4, v5, v6, v4
	v_max_f32_e32 v5, v34, v35
	v_max_f32_e32 v6, v24, v25
	v_max3_f32 v4, v5, v6, v4
	v_max_f32_e32 v5, v28, v29
	v_max_f32_e32 v6, v16, v17
	v_max3_f32 v4, v5, v6, v4
	v_max_f32_e32 v5, v22, v23
	v_max_f32_e32 v6, v12, v13
	v_max3_f32 v4, v5, v6, v4
	v_max_f32_e32 v5, v14, v15
	v_max_f32_e32 v6, v8, v9
	v_max3_f32 v4, v5, v6, v4
	v_max_f32_e32 v5, v20, v21
	v_max_f32_e32 v6, v10, v11
	v_max3_f32 v4, v5, v6, v4
	v_max_f32_e32 v5, v32, v33
	v_max_f32_e32 v6, v18, v19
	v_max3_f32 v4, v5, v6, v4
	v_max_f32_e32 v5, v38, v39
	v_max_f32_e32 v6, v26, v27
	v_max3_f32 v4, v5, v6, v4
	v_max_f32_e32 v5, v48, v49
	v_max_f32_e32 v6, v44, v45
	v_pk_mul_f32 v[2:3], v[2:3], s[18:19] op_sel_hi:[1,0]
	v_max3_f32 v4, v5, v6, v4
	v_max_f32_e32 v5, v58, v59
	v_max_f32_e32 v6, v54, v55
	v_max3_f32 v4, v5, v6, v4
	v_max_f32_e32 v5, v2, v3
	v_max_f32_e32 v6, v0, v1
	v_max3_f32 v5, v5, v6, v4
	v_and_b32_e32 v6, 64, v183
	v_xor_b32_e32 v4, 16, v183
	v_add_u32_e32 v6, 64, v6
	v_cmp_lt_i32_e32 vcc, v4, v6
	s_nop 1
	v_cndmask_b32_e32 v4, v183, v4, vcc
	v_lshlrev_b32_e32 v4, 2, v4
	ds_bpermute_b32 v7, v4, v5
	s_waitcnt lgkmcnt(0)
	v_max_f32_e32 v7, v7, v7
	v_max_f32_e32 v7, v5, v7
	v_xor_b32_e32 v5, 32, v183
	v_cmp_lt_i32_e32 vcc, v5, v6
	s_nop 1
	v_cndmask_b32_e32 v5, v183, v5, vcc
	v_lshlrev_b32_e32 v5, 2, v5
	ds_bpermute_b32 v6, v5, v7
	s_waitcnt lgkmcnt(0)
; __device__ __forceinline__ void phase_attn(const Args& a, unsigned char* smem, int tid, int lane, int wave, bf16_t* Yout) {
;     ...
;             float l = 0.f;
; #pragma unroll
;             for (int t = 0; t < 32; ++t) {
; #pragma unroll
;                 for (int e = 0; e < 4; ++e) { const float p = __expf(st[t][e] - mx); st[t][e] = p; l += p; } }
	v_max_f32_e32 v6, v6, v6
	v_max_f32_e32 v6, v7, v6
	v_sub_f32_e32 v68, v68, v6
	v_mul_f32_e32 v68, 0x3fb8aa3b, v68
	v_exp_f32_e32 v185, v68
	v_sub_f32_e32 v68, v71, v6
	v_mul_f32_e32 v68, 0x3fb8aa3b, v68
	v_exp_f32_e32 v186, v68
	v_sub_f32_e32 v68, v70, v6
	v_mul_f32_e32 v68, 0x3fb8aa3b, v68
	v_exp_f32_e32 v187, v68
	v_sub_f32_e32 v68, v73, v6
	v_mul_f32_e32 v68, 0x3fb8aa3b, v68
	v_exp_f32_e32 v188, v68
	v_sub_f32_e32 v68, v72, v6
	v_mul_f32_e32 v68, 0x3fb8aa3b, v68
	v_exp_f32_e32 v189, v68
	v_sub_f32_e32 v68, v75, v6
	v_mul_f32_e32 v68, 0x3fb8aa3b, v68
	v_exp_f32_e32 v190, v68
	v_sub_f32_e32 v68, v74, v6
	v_mul_f32_e32 v68, 0x3fb8aa3b, v68
	v_exp_f32_e32 v191, v68
	v_sub_f32_e32 v68, v77, v6
	v_mul_f32_e32 v68, 0x3fb8aa3b, v68
	v_exp_f32_e32 v192, v68
	v_sub_f32_e32 v68, v76, v6
	v_mul_f32_e32 v68, 0x3fb8aa3b, v68
	v_exp_f32_e32 v193, v68
	v_sub_f32_e32 v68, v79, v6
	v_mul_f32_e32 v68, 0x3fb8aa3b, v68
	v_exp_f32_e32 v194, v68
	v_sub_f32_e32 v68, v78, v6
	v_mul_f32_e32 v68, 0x3fb8aa3b, v68
	v_exp_f32_e32 v195, v68
	v_sub_f32_e32 v68, v81, v6
	v_mul_f32_e32 v68, 0x3fb8aa3b, v68
	v_exp_f32_e32 v196, v68
	v_sub_f32_e32 v68, v80, v6
	v_mul_f32_e32 v68, 0x3fb8aa3b, v68
	v_exp_f32_e32 v197, v68
	v_sub_f32_e32 v68, v83, v6
	v_mul_f32_e32 v68, 0x3fb8aa3b, v68
	v_exp_f32_e32 v198, v68
	v_sub_f32_e32 v68, v82, v6
	v_sub_f32_e32 v7, v69, v6
	v_mul_f32_e32 v68, 0x3fb8aa3b, v68
	v_mul_f32_e32 v7, 0x3fb8aa3b, v7
	v_exp_f32_e32 v199, v68
	v_sub_f32_e32 v68, v85, v6
	v_exp_f32_e32 v184, v7
	v_mul_f32_e32 v68, 0x3fb8aa3b, v68
	v_exp_f32_e32 v200, v68
	v_sub_f32_e32 v68, v84, v6
	v_mul_f32_e32 v68, 0x3fb8aa3b, v68
	v_exp_f32_e32 v201, v68
	v_sub_f32_e32 v68, v87, v6
	v_add_f32_e32 v7, 0, v184
	v_mul_f32_e32 v68, 0x3fb8aa3b, v68
	v_add_f32_e32 v7, v185, v7
	v_exp_f32_e32 v202, v68
	v_sub_f32_e32 v68, v86, v6
	v_add_f32_e32 v7, v186, v7
	v_mul_f32_e32 v68, 0x3fb8aa3b, v68
	v_add_f32_e32 v7, v187, v7
	v_exp_f32_e32 v203, v68
	v_sub_f32_e32 v68, v89, v6
	v_add_f32_e32 v7, v188, v7
	v_mul_f32_e32 v68, 0x3fb8aa3b, v68
	v_add_f32_e32 v7, v189, v7
	v_exp_f32_e32 v204, v68
	v_sub_f32_e32 v68, v88, v6
	v_add_f32_e32 v7, v190, v7
	v_mul_f32_e32 v68, 0x3fb8aa3b, v68
	v_add_f32_e32 v7, v191, v7
	v_exp_f32_e32 v205, v68
	v_sub_f32_e32 v68, v91, v6
	v_add_f32_e32 v7, v192, v7
	v_mul_f32_e32 v68, 0x3fb8aa3b, v68
	v_add_f32_e32 v7, v193, v7
	v_exp_f32_e32 v206, v68
	v_sub_f32_e32 v68, v90, v6
	v_add_f32_e32 v7, v194, v7
	v_mul_f32_e32 v68, 0x3fb8aa3b, v68
	v_add_f32_e32 v7, v195, v7
	v_exp_f32_e32 v207, v68
	v_sub_f32_e32 v68, v93, v6
	v_add_f32_e32 v7, v196, v7
	v_mul_f32_e32 v68, 0x3fb8aa3b, v68
	v_add_f32_e32 v7, v197, v7
	v_exp_f32_e32 v208, v68
	v_sub_f32_e32 v68, v92, v6
	v_add_f32_e32 v7, v198, v7
	v_mul_f32_e32 v68, 0x3fb8aa3b, v68
	v_add_f32_e32 v7, v199, v7
	v_exp_f32_e32 v209, v68
	v_sub_f32_e32 v68, v95, v6
	v_add_f32_e32 v7, v200, v7
	v_mul_f32_e32 v68, 0x3fb8aa3b, v68
	v_add_f32_e32 v7, v201, v7
	v_exp_f32_e32 v210, v68
	v_sub_f32_e32 v68, v94, v6
	v_add_f32_e32 v7, v202, v7
	v_mul_f32_e32 v68, 0x3fb8aa3b, v68
	v_add_f32_e32 v7, v203, v7
	v_exp_f32_e32 v211, v68
	v_sub_f32_e32 v68, v97, v6
	v_add_f32_e32 v7, v204, v7
	v_mul_f32_e32 v68, 0x3fb8aa3b, v68
	v_add_f32_e32 v7, v205, v7
	v_exp_f32_e32 v212, v68
	v_sub_f32_e32 v68, v96, v6
	v_add_f32_e32 v7, v206, v7
	v_mul_f32_e32 v68, 0x3fb8aa3b, v68
	v_add_f32_e32 v7, v207, v7
	v_exp_f32_e32 v213, v68
	v_sub_f32_e32 v68, v99, v6
	v_add_f32_e32 v7, v208, v7
	v_mul_f32_e32 v68, 0x3fb8aa3b, v68
	v_add_f32_e32 v7, v209, v7
	v_exp_f32_e32 v214, v68
	v_sub_f32_e32 v68, v98, v6
	v_add_f32_e32 v7, v210, v7
	v_mul_f32_e32 v68, 0x3fb8aa3b, v68
	v_add_f32_e32 v7, v211, v7
	v_exp_f32_e32 v215, v68
	v_add_f32_e32 v7, v212, v7
	v_add_f32_e32 v7, v213, v7
	v_add_f32_e32 v7, v214, v7
	v_add_f32_e32 v68, v215, v7
	v_sub_f32_e32 v7, v101, v6
	v_mul_f32_e32 v7, 0x3fb8aa3b, v7
	v_exp_f32_e32 v7, v7
	v_sub_f32_e32 v93, v219, v6
	v_mul_f32_e32 v93, 0x3fb8aa3b, v93
	v_sub_f32_e32 v94, v222, v6
	v_add_f32_e32 v69, v7, v68
	v_sub_f32_e32 v68, v100, v6
	v_mul_f32_e32 v68, 0x3fb8aa3b, v68
	v_exp_f32_e32 v68, v68
	v_exp_f32_e32 v93, v93
	v_mul_f32_e32 v94, 0x3fb8aa3b, v94
	v_sub_f32_e32 v95, v221, v6
	v_add_f32_e32 v70, v68, v69
	v_sub_f32_e32 v69, v103, v6
	v_mul_f32_e32 v69, 0x3fb8aa3b, v69
	v_exp_f32_e32 v69, v69
	v_exp_f32_e32 v94, v94
	v_mul_f32_e32 v95, 0x3fb8aa3b, v95
	v_sub_f32_e32 v96, v224, v6
	v_add_f32_e32 v71, v69, v70
	v_sub_f32_e32 v70, v102, v6
	v_mul_f32_e32 v70, 0x3fb8aa3b, v70
	v_exp_f32_e32 v70, v70
	v_exp_f32_e32 v95, v95
	v_mul_f32_e32 v96, 0x3fb8aa3b, v96
	v_sub_f32_e32 v97, v223, v6
	v_add_f32_e32 v72, v70, v71
	v_sub_f32_e32 v71, v105, v6
	v_mul_f32_e32 v71, 0x3fb8aa3b, v71
	v_exp_f32_e32 v71, v71
	v_exp_f32_e32 v96, v96
	v_mul_f32_e32 v97, 0x3fb8aa3b, v97
	v_sub_f32_e32 v98, v226, v6
	v_add_f32_e32 v73, v71, v72
	v_sub_f32_e32 v72, v104, v6
	v_mul_f32_e32 v72, 0x3fb8aa3b, v72
	v_exp_f32_e32 v72, v72
	v_exp_f32_e32 v97, v97
	v_mul_f32_e32 v98, 0x3fb8aa3b, v98
	v_sub_f32_e32 v99, v225, v6
	v_add_f32_e32 v74, v72, v73
	v_sub_f32_e32 v73, v107, v6
	v_mul_f32_e32 v73, 0x3fb8aa3b, v73
	v_exp_f32_e32 v73, v73
	v_exp_f32_e32 v98, v98
	v_mul_f32_e32 v99, 0x3fb8aa3b, v99
	v_sub_f32_e32 v66, v66, v6
	v_add_f32_e32 v75, v73, v74
	v_sub_f32_e32 v74, v106, v6
	v_mul_f32_e32 v74, 0x3fb8aa3b, v74
	v_exp_f32_e32 v74, v74
	v_exp_f32_e32 v99, v99
	v_mul_f32_e32 v66, 0x3fb8aa3b, v66
	v_sub_f32_e32 v67, v67, v6
	v_add_f32_e32 v76, v74, v75
	v_sub_f32_e32 v75, v109, v6
	v_mul_f32_e32 v75, 0x3fb8aa3b, v75
	v_exp_f32_e32 v75, v75
	v_exp_f32_e32 v66, v66
	v_mul_f32_e32 v67, 0x3fb8aa3b, v67
	v_sub_f32_e32 v60, v60, v6
	v_add_f32_e32 v77, v75, v76
; __device__ __forceinline__ void phase_attn(const Args& a, unsigned char* smem, int tid, int lane, int wave, bf16_t* Yout) {
;     ...
;             float l = 0.f;
; #pragma unroll
;             for (int t = 0; t < 32; ++t) {
; #pragma unroll
;                 for (int e = 0; e < 4; ++e) { const float p = __expf(st[t][e] - mx); st[t][e] = p; l += p; } }
	v_sub_f32_e32 v76, v108, v6
	v_mul_f32_e32 v76, 0x3fb8aa3b, v76
	v_exp_f32_e32 v76, v76
	v_exp_f32_e32 v67, v67
	v_mul_f32_e32 v60, 0x3fb8aa3b, v60
	v_sub_f32_e32 v61, v61, v6
	v_add_f32_e32 v78, v76, v77
	v_sub_f32_e32 v77, v111, v6
	v_mul_f32_e32 v77, 0x3fb8aa3b, v77
	v_exp_f32_e32 v77, v77
	v_exp_f32_e32 v60, v60
	v_mul_f32_e32 v61, 0x3fb8aa3b, v61
	v_sub_f32_e32 v64, v64, v6
	v_add_f32_e32 v79, v77, v78
	v_sub_f32_e32 v78, v110, v6
	v_mul_f32_e32 v78, 0x3fb8aa3b, v78
	v_exp_f32_e32 v78, v78
	v_exp_f32_e32 v61, v61
	v_mul_f32_e32 v64, 0x3fb8aa3b, v64
	v_sub_f32_e32 v65, v65, v6
	v_add_f32_e32 v80, v78, v79
	v_sub_f32_e32 v79, v148, v6
	v_mul_f32_e32 v79, 0x3fb8aa3b, v79
	v_exp_f32_e32 v79, v79
	v_exp_f32_e32 v64, v64
	v_mul_f32_e32 v65, 0x3fb8aa3b, v65
	v_sub_f32_e32 v56, v56, v6
	v_add_f32_e32 v81, v79, v80
	v_sub_f32_e32 v80, v147, v6
	v_mul_f32_e32 v80, 0x3fb8aa3b, v80
	v_exp_f32_e32 v80, v80
	v_exp_f32_e32 v65, v65
	v_mul_f32_e32 v56, 0x3fb8aa3b, v56
	v_sub_f32_e32 v57, v57, v6
	v_add_f32_e32 v82, v80, v81
	v_sub_f32_e32 v81, v150, v6
	v_mul_f32_e32 v81, 0x3fb8aa3b, v81
	v_exp_f32_e32 v81, v81
	v_exp_f32_e32 v56, v56
	v_mul_f32_e32 v57, 0x3fb8aa3b, v57
	v_sub_f32_e32 v62, v62, v6
	v_add_f32_e32 v83, v81, v82
	v_sub_f32_e32 v82, v149, v6
	v_mul_f32_e32 v82, 0x3fb8aa3b, v82
	v_exp_f32_e32 v82, v82
	v_exp_f32_e32 v57, v57
	v_mul_f32_e32 v62, 0x3fb8aa3b, v62
	v_sub_f32_e32 v63, v63, v6
	v_add_f32_e32 v84, v82, v83
	v_sub_f32_e32 v83, v152, v6
	v_mul_f32_e32 v83, 0x3fb8aa3b, v83
	v_exp_f32_e32 v83, v83
	v_exp_f32_e32 v62, v62
	v_mul_f32_e32 v63, 0x3fb8aa3b, v63
	v_sub_f32_e32 v50, v50, v6
	v_add_f32_e32 v85, v83, v84
	v_sub_f32_e32 v84, v151, v6
	v_mul_f32_e32 v84, 0x3fb8aa3b, v84
	v_exp_f32_e32 v84, v84
	v_exp_f32_e32 v63, v63
	v_mul_f32_e32 v50, 0x3fb8aa3b, v50
	v_sub_f32_e32 v51, v51, v6
	v_add_f32_e32 v86, v84, v85
	v_sub_f32_e32 v85, v154, v6
	v_mul_f32_e32 v85, 0x3fb8aa3b, v85
	v_exp_f32_e32 v85, v85
	v_exp_f32_e32 v50, v50
	v_mul_f32_e32 v51, 0x3fb8aa3b, v51
	v_sub_f32_e32 v52, v52, v6
	v_add_f32_e32 v87, v85, v86
	v_sub_f32_e32 v86, v153, v6
	v_mul_f32_e32 v86, 0x3fb8aa3b, v86
	v_exp_f32_e32 v86, v86
	v_exp_f32_e32 v51, v51
	v_mul_f32_e32 v52, 0x3fb8aa3b, v52
	v_sub_f32_e32 v53, v53, v6
	v_add_f32_e32 v88, v86, v87
	v_sub_f32_e32 v87, v216, v6
	v_mul_f32_e32 v87, 0x3fb8aa3b, v87
	v_exp_f32_e32 v87, v87
	v_exp_f32_e32 v52, v52
	v_mul_f32_e32 v53, 0x3fb8aa3b, v53
	v_sub_f32_e32 v42, v42, v6
	v_add_f32_e32 v89, v87, v88
	v_sub_f32_e32 v88, v155, v6
	v_mul_f32_e32 v88, 0x3fb8aa3b, v88
	v_exp_f32_e32 v88, v88
	v_exp_f32_e32 v53, v53
	v_mul_f32_e32 v42, 0x3fb8aa3b, v42
	v_sub_f32_e32 v43, v43, v6
	v_add_f32_e32 v90, v88, v89
	v_sub_f32_e32 v89, v218, v6
	v_mul_f32_e32 v89, 0x3fb8aa3b, v89
	v_exp_f32_e32 v89, v89
	v_exp_f32_e32 v42, v42
	v_mul_f32_e32 v43, 0x3fb8aa3b, v43
	v_sub_f32_e32 v46, v46, v6
	v_add_f32_e32 v91, v89, v90
	v_sub_f32_e32 v90, v217, v6
	v_mul_f32_e32 v90, 0x3fb8aa3b, v90
	v_exp_f32_e32 v90, v90
	v_exp_f32_e32 v43, v43
	v_mul_f32_e32 v46, 0x3fb8aa3b, v46
	v_sub_f32_e32 v47, v47, v6
	v_add_f32_e32 v92, v90, v91
	v_sub_f32_e32 v91, v220, v6
	v_mul_f32_e32 v91, 0x3fb8aa3b, v91
	v_exp_f32_e32 v91, v91
	v_exp_f32_e32 v46, v46
	v_mul_f32_e32 v47, 0x3fb8aa3b, v47
	v_sub_f32_e32 v36, v36, v6
	v_add_f32_e32 v92, v91, v92
	v_add_f32_e32 v92, v93, v92
	v_add_f32_e32 v92, v94, v92
	v_add_f32_e32 v92, v95, v92
	v_add_f32_e32 v92, v96, v92
	v_add_f32_e32 v92, v97, v92
	v_add_f32_e32 v92, v98, v92
	v_add_f32_e32 v92, v99, v92
	v_add_f32_e32 v92, v66, v92
	v_add_f32_e32 v92, v67, v92
	v_add_f32_e32 v92, v60, v92
	v_add_f32_e32 v92, v61, v92
	v_add_f32_e32 v92, v64, v92
	v_add_f32_e32 v92, v65, v92
	v_add_f32_e32 v92, v56, v92
	v_add_f32_e32 v92, v57, v92
	v_add_f32_e32 v92, v62, v92
	v_add_f32_e32 v92, v63, v92
	v_add_f32_e32 v92, v50, v92
	v_add_f32_e32 v92, v51, v92
	v_add_f32_e32 v92, v52, v92
	v_add_f32_e32 v92, v53, v92
	v_exp_f32_e32 v47, v47
	v_mul_f32_e32 v36, 0x3fb8aa3b, v36
	v_sub_f32_e32 v37, v37, v6
	v_sub_f32_e32 v9, v9, v6
	v_add_f32_e32 v92, v42, v92
	v_exp_f32_e32 v100, v36
	v_mul_f32_e32 v37, 0x3fb8aa3b, v37
	v_sub_f32_e32 v40, v40, v6
	v_mul_f32_e32 v9, 0x3fb8aa3b, v9
	v_add_f32_e32 v92, v43, v92
	v_exp_f32_e32 v37, v37
	v_mul_f32_e32 v40, 0x3fb8aa3b, v40
	v_sub_f32_e32 v41, v41, v6
	v_exp_f32_e32 v105, v9
	v_sub_f32_e32 v9, v20, v6
	v_add_f32_e32 v92, v46, v92
	v_exp_f32_e32 v40, v40
	v_mul_f32_e32 v41, 0x3fb8aa3b, v41
	v_sub_f32_e32 v30, v30, v6
	v_mul_f32_e32 v9, 0x3fb8aa3b, v9
	v_add_f32_e32 v92, v47, v92
	v_exp_f32_e32 v41, v41
	v_mul_f32_e32 v30, 0x3fb8aa3b, v30
	v_sub_f32_e32 v31, v31, v6
	v_exp_f32_e32 v20, v9
	v_sub_f32_e32 v9, v21, v6
	v_add_f32_e32 v36, v100, v92
	v_exp_f32_e32 v30, v30
	v_mul_f32_e32 v31, 0x3fb8aa3b, v31
	v_sub_f32_e32 v34, v34, v6
	v_mul_f32_e32 v9, 0x3fb8aa3b, v9
	v_add_f32_e32 v36, v37, v36
	v_exp_f32_e32 v31, v31
	v_mul_f32_e32 v34, 0x3fb8aa3b, v34
	v_sub_f32_e32 v35, v35, v6
	v_exp_f32_e32 v21, v9
	v_sub_f32_e32 v9, v10, v6
	v_add_f32_e32 v36, v40, v36
	v_exp_f32_e32 v34, v34
	v_mul_f32_e32 v35, 0x3fb8aa3b, v35
	v_sub_f32_e32 v24, v24, v6
	v_mul_f32_e32 v9, 0x3fb8aa3b, v9
	v_add_f32_e32 v36, v41, v36
	v_exp_f32_e32 v35, v35
	v_mul_f32_e32 v24, 0x3fb8aa3b, v24
	v_sub_f32_e32 v25, v25, v6
	v_exp_f32_e32 v106, v9
	v_sub_f32_e32 v9, v11, v6
	v_add_f32_e32 v36, v30, v36
	v_exp_f32_e32 v24, v24
	v_mul_f32_e32 v25, 0x3fb8aa3b, v25
	v_sub_f32_e32 v28, v28, v6
	v_mul_f32_e32 v9, 0x3fb8aa3b, v9
	v_add_f32_e32 v36, v31, v36
	v_exp_f32_e32 v25, v25
	v_mul_f32_e32 v28, 0x3fb8aa3b, v28
	v_sub_f32_e32 v29, v29, v6
	v_exp_f32_e32 v107, v9
	v_sub_f32_e32 v9, v32, v6
	v_add_f32_e32 v36, v34, v36
; __device__ __forceinline__ unsigned pk2(float lo, float hi) { const f32x2 v = {lo, hi}; const bf16x2_t b = __builtin_convertvector(v, bf16x2_t); return __builtin_bit_cast(unsigned, b); }
; #define ATT_VLOAD16(bt, dstb) do { _Pragma("unroll") for (int pp_ = 0; pp_ < 4; ++pp_) { \
;                 const size_t tokb_ = (size_t)b * 16384 + (rs + (bt) * 4 + pp_) * 64 + kc0 + 8 * g; \
;                 _Pragma("unroll") for (int mt_ = 0; mt_ < 4; ++mt_) vb2[dstb][pp_ * 4 + mt_] = *(const bf16x8*)(AVT + (size_t)(h * 64 + mt_ * 16 + q16) * MR + tokb_); } } while (0)
; __device__ __forceinline__ void phase_attn(const Args& a, unsigned char* smem, int tid, int lane, int wave, bf16_t* Yout) {
;     ...
;             for (int t = 0; t < 32; ++t) {
; #pragma unroll
;                 for (int e = 0; e < 4; ++e) { const float p = __expf(st[t][e] - mx); st[t][e] = p; l += p; } }
;             l += __shfl_xor(l, 16); l += __shfl_xor(l, 32);
;             bf16x8 pb[16];
; #pragma unroll
;             for (int p = 0; p < 16; ++p) { u32x4 pw; pw.x = pk2(st[2 * p][0], st[2 * p][1]); pw.y = pk2(st[2 * p][2], st[2 * p][3]); pw.z = pk2(st[2 * p + 1][0], st[2 * p + 1][1]); pw.w = pk2(st[2 * p + 1][2], st[2 * p + 1][3]);
;                 pb[p] = __builtin_bit_cast(bf16x8, pw); }
;             f32x4 o[4];
; #pragma unroll
;             for (int mt = 0; mt < 4; ++mt) o[mt] = (f32x4){0.f, 0.f, 0.f, 0.f};
;             bf16x8 vb2[1][16];
;     ...
;             ATT_VLOAD16(0, 0);
	v_exp_f32_e32 v28, v28
	v_mul_f32_e32 v29, 0x3fb8aa3b, v29
	v_sub_f32_e32 v16, v16, v6
	v_mul_f32_e32 v9, 0x3fb8aa3b, v9
	v_add_f32_e32 v36, v35, v36
	v_exp_f32_e32 v29, v29
	v_mul_f32_e32 v16, 0x3fb8aa3b, v16
	v_sub_f32_e32 v17, v17, v6
	v_exp_f32_e32 v147, v9
	v_sub_f32_e32 v9, v33, v6
	v_add_f32_e32 v36, v24, v36
	v_exp_f32_e32 v16, v16
	v_mul_f32_e32 v17, 0x3fb8aa3b, v17
	v_sub_f32_e32 v22, v22, v6
	v_mul_f32_e32 v9, 0x3fb8aa3b, v9
	v_add_f32_e32 v36, v25, v36
	v_exp_f32_e32 v17, v17
	v_mul_f32_e32 v22, 0x3fb8aa3b, v22
	v_sub_f32_e32 v23, v23, v6
	v_sub_f32_e32 v13, v13, v6
	v_exp_f32_e32 v148, v9
	v_sub_f32_e32 v9, v18, v6
	v_add_f32_e32 v36, v28, v36
	v_exp_f32_e32 v22, v22
	v_mul_f32_e32 v23, 0x3fb8aa3b, v23
	v_sub_f32_e32 v12, v12, v6
	v_mul_f32_e32 v13, 0x3fb8aa3b, v13
	v_mul_f32_e32 v9, 0x3fb8aa3b, v9
	v_add_f32_e32 v36, v29, v36
	v_exp_f32_e32 v23, v23
	v_mul_f32_e32 v12, 0x3fb8aa3b, v12
	v_exp_f32_e32 v101, v13
	v_sub_f32_e32 v13, v14, v6
	v_exp_f32_e32 v18, v9
	v_sub_f32_e32 v9, v19, v6
	v_add_f32_e32 v36, v16, v36
	v_exp_f32_e32 v92, v12
	v_mul_f32_e32 v13, 0x3fb8aa3b, v13
	v_mul_f32_e32 v9, 0x3fb8aa3b, v9
	v_add_f32_e32 v36, v17, v36
	v_exp_f32_e32 v102, v13
	v_sub_f32_e32 v13, v15, v6
	v_exp_f32_e32 v19, v9
	v_sub_f32_e32 v9, v38, v6
	v_add_f32_e32 v36, v22, v36
	v_mul_f32_e32 v13, 0x3fb8aa3b, v13
	v_sub_f32_e32 v8, v8, v6
	v_mul_f32_e32 v9, 0x3fb8aa3b, v9
	v_add_f32_e32 v36, v23, v36
	v_exp_f32_e32 v103, v13
	v_mul_f32_e32 v8, 0x3fb8aa3b, v8
	v_exp_f32_e32 v149, v9
	v_sub_f32_e32 v9, v39, v6
	v_add_f32_e32 v12, v92, v36
	v_exp_f32_e32 v104, v8
	v_mul_f32_e32 v9, 0x3fb8aa3b, v9
	v_add_f32_e32 v12, v101, v12
	v_exp_f32_e32 v150, v9
	v_sub_f32_e32 v9, v26, v6
	v_add_f32_e32 v12, v102, v12
	v_mul_f32_e32 v9, 0x3fb8aa3b, v9
	v_add_f32_e32 v12, v103, v12
	v_exp_f32_e32 v151, v9
	v_sub_f32_e32 v9, v27, v6
	v_add_f32_e32 v8, v104, v12
	v_mul_f32_e32 v9, 0x3fb8aa3b, v9
	v_add_f32_e32 v8, v105, v8
	v_exp_f32_e32 v152, v9
	v_sub_f32_e32 v9, v48, v6
	v_add_f32_e32 v8, v20, v8
	v_mul_f32_e32 v9, 0x3fb8aa3b, v9
	v_add_f32_e32 v8, v21, v8
	v_exp_f32_e32 v153, v9
	v_sub_f32_e32 v9, v49, v6
	v_add_f32_e32 v8, v106, v8
	v_mul_f32_e32 v9, 0x3fb8aa3b, v9
	v_add_f32_e32 v8, v107, v8
	v_exp_f32_e32 v154, v9
	v_sub_f32_e32 v9, v44, v6
	v_add_f32_e32 v8, v147, v8
	v_mul_f32_e32 v9, 0x3fb8aa3b, v9
	v_add_f32_e32 v8, v148, v8
	v_exp_f32_e32 v44, v9
	v_sub_f32_e32 v9, v45, v6
	v_add_f32_e32 v8, v18, v8
	v_mul_f32_e32 v9, 0x3fb8aa3b, v9
	v_add_f32_e32 v8, v19, v8
	v_exp_f32_e32 v45, v9
	v_sub_f32_e32 v9, v58, v6
	v_add_f32_e32 v8, v149, v8
	v_mul_f32_e32 v9, 0x3fb8aa3b, v9
	v_add_f32_e32 v8, v150, v8
	v_exp_f32_e32 v58, v9
	v_sub_f32_e32 v9, v59, v6
	v_add_f32_e32 v8, v151, v8
	v_mul_f32_e32 v9, 0x3fb8aa3b, v9
	v_add_f32_e32 v8, v152, v8
	v_exp_f32_e32 v59, v9
	v_sub_f32_e32 v9, v54, v6
	v_add_f32_e32 v8, v153, v8
	v_mul_f32_e32 v9, 0x3fb8aa3b, v9
	v_add_f32_e32 v8, v154, v8
	v_exp_f32_e32 v54, v9
	v_sub_f32_e32 v9, v55, v6
	v_add_f32_e32 v8, v44, v8
	v_mul_f32_e32 v9, 0x3fb8aa3b, v9
	v_sub_f32_e32 v2, v2, v6
	v_add_f32_e32 v8, v45, v8
	v_exp_f32_e32 v55, v9
	v_mul_f32_e32 v2, 0x3fb8aa3b, v2
	v_sub_f32_e32 v3, v3, v6
	v_add_f32_e32 v8, v58, v8
	v_exp_f32_e32 v155, v2
	v_mul_f32_e32 v3, 0x3fb8aa3b, v3
	v_sub_f32_e32 v0, v0, v6
	v_add_f32_e32 v8, v59, v8
	v_exp_f32_e32 v218, v3
	v_mul_f32_e32 v0, 0x3fb8aa3b, v0
	v_sub_f32_e32 v1, v1, v6
	v_add_f32_e32 v8, v54, v8
	v_exp_f32_e32 v219, v0
	v_mul_f32_e32 v1, 0x3fb8aa3b, v1
	v_add_f32_e32 v8, v55, v8
	v_exp_f32_e32 v220, v1
	v_add_f32_e32 v2, v155, v8
	v_add_f32_e32 v2, v218, v2
	v_cvt_pk_bf16_f32 v38, v40, v41
	v_lshl_add_u64 v[40:41], v[132:133], 0, v[114:115]
	v_add_f32_e32 v0, v219, v2
	v_cvt_pk_bf16_f32 v26, v147, v148
	v_lshl_add_u64 v[40:41], v[40:41], 0, s[12:13]
	v_mov_b32_e32 v147, v115
	v_add_f32_e32 v0, v220, v0
	v_cvt_pk_bf16_f32 v32, v34, v35
	v_cvt_pk_bf16_f32 v34, v28, v29
	v_cvt_pk_bf16_f32 v28, v22, v23
	v_cvt_pk_bf16_f32 v27, v18, v19
	v_cvt_pk_bf16_f32 v22, v153, v154
	v_cvt_pk_bf16_f32 v18, v155, v218
	v_lshl_add_u64 v[154:155], v[40:41], 0, v[146:147]
	ds_bpermute_b32 v1, v4, v0
	v_cvt_pk_bf16_f32 v33, v24, v25
	v_cvt_pk_bf16_f32 v24, v20, v21
	v_cvt_pk_bf16_f32 v21, v151, v152
	v_add_co_u32_e32 v152, vcc, s48, v154
	v_cvt_pk_bf16_f32 v20, v149, v150
	s_nop 0
	v_addc_co_u32_e32 v153, vcc, 0, v155, vcc
	v_add_co_u32_e32 v150, vcc, s49, v154
	s_waitcnt lgkmcnt(0)
	v_add_f32_e32 v216, v0, v1
	v_addc_co_u32_e32 v151, vcc, 0, v155, vcc
	v_add_co_u32_e32 v148, vcc, s50, v154
	ds_bpermute_b32 v217, v5, v216
	s_nop 0
	v_addc_co_u32_e32 v149, vcc, 0, v155, vcc
	v_cvt_pk_bf16_f32 v12, v7, v68
	v_cvt_pk_bf16_f32 v13, v69, v70
	v_cvt_pk_bf16_f32 v14, v71, v72
	v_cvt_pk_bf16_f32 v15, v73, v74
	v_cvt_pk_bf16_f32 v8, v75, v76
	v_cvt_pk_bf16_f32 v9, v77, v78
	v_cvt_pk_bf16_f32 v10, v79, v80
	v_cvt_pk_bf16_f32 v11, v81, v82
	v_cvt_pk_bf16_f32 v4, v83, v84
	v_cvt_pk_bf16_f32 v5, v85, v86
	v_cvt_pk_bf16_f32 v6, v87, v88
	v_cvt_pk_bf16_f32 v7, v89, v90
	v_cvt_pk_bf16_f32 v0, v91, v93
	v_cvt_pk_bf16_f32 v1, v94, v95
	v_cvt_pk_bf16_f32 v2, v96, v97
	v_cvt_pk_bf16_f32 v3, v98, v99
	v_cvt_pk_bf16_f32 v108, v66, v67
	v_cvt_pk_bf16_f32 v109, v60, v61
	v_cvt_pk_bf16_f32 v110, v64, v65
	v_cvt_pk_bf16_f32 v111, v56, v57
	v_cvt_pk_bf16_f32 v48, v62, v63
	v_cvt_pk_bf16_f32 v49, v50, v51
	v_cvt_pk_bf16_f32 v50, v52, v53
	v_cvt_pk_bf16_f32 v51, v42, v43
	v_cvt_pk_bf16_f32 v36, v46, v47
	v_cvt_pk_bf16_f32 v37, v100, v37
	v_cvt_pk_bf16_f32 v39, v30, v31
	v_cvt_pk_bf16_f32 v35, v16, v17
	v_cvt_pk_bf16_f32 v29, v92, v101
	v_cvt_pk_bf16_f32 v30, v102, v103
	v_cvt_pk_bf16_f32 v31, v104, v105
	v_cvt_pk_bf16_f32 v25, v106, v107
	v_cvt_pk_bf16_f32 v23, v44, v45
	v_cvt_pk_bf16_f32 v16, v58, v59
	v_cvt_pk_bf16_f32 v17, v54, v55
	global_load_dwordx4 v[40:43], v[154:155], off
	global_load_dwordx4 v[44:47], v[152:153], off
	global_load_dwordx4 v[52:55], v[150:151], off
	global_load_dwordx4 v[56:59], v[148:149], off
	global_load_dwordx4 v[60:63], v[154:155], off offset:128
	global_load_dwordx4 v[64:67], v[152:153], off offset:128
	global_load_dwordx4 v[68:71], v[150:151], off offset:128
	global_load_dwordx4 v[72:75], v[148:149], off offset:128
	global_load_dwordx4 v[76:79], v[154:155], off offset:256
	global_load_dwordx4 v[80:83], v[152:153], off offset:256
	global_load_dwordx4 v[84:87], v[150:151], off offset:256
	global_load_dwordx4 v[88:91], v[148:149], off offset:256
	global_load_dwordx4 v[92:95], v[154:155], off offset:384
	global_load_dwordx4 v[96:99], v[152:153], off offset:384
	global_load_dwordx4 v[100:103], v[150:151], off offset:384
	global_load_dwordx4 v[104:107], v[148:149], off offset:384
	v_cvt_pk_bf16_f32 v19, v219, v220
	ds_read_b128 v[218:221], v169 offset:36864
	ds_read_b128 v[222:225], v169 offset:45312
	ds_read_b128 v[226:229], v169 offset:53760
	ds_read_b128 v[230:233], v170 offset:36864
	s_waitcnt lgkmcnt(3)
; __device__ __forceinline__ f32x4 mfma16(bf16x8 a, bf16x8 b, f32x4 c) { return __builtin_amdgcn_mfma_f32_16x16x32_bf16(a, b, c, 0, 0, 0); }
; #define ATT_VLOAD16(bt, dstb) do { _Pragma("unroll") for (int pp_ = 0; pp_ < 4; ++pp_) { \
;                 const size_t tokb_ = (size_t)b * 16384 + (rs + (bt) * 4 + pp_) * 64 + kc0 + 8 * g; \
;                 _Pragma("unroll") for (int mt_ = 0; mt_ < 4; ++mt_) vb2[dstb][pp_ * 4 + mt_] = *(const bf16x8*)(AVT + (size_t)(h * 64 + mt_ * 16 + q16) * MR + tokb_); } } while (0)
; __device__ __forceinline__ void phase_attn(const Args& a, unsigned char* smem, int tid, int lane, int wave, bf16_t* Yout) {
;     ...
; #pragma unroll
;             for (int p = 8; p < 16; ++p) {
; #pragma unroll
;                 for (int mt = 0; mt < 4; ++mt) o[mt] = mfma16(*(const bf16x8*)(Vs + (mt * 16 + q16) * 264 + (p - 8) * 32 + 8 * g), pb[p], o[mt]);
;             }
;             asm volatile("" ::: "memory");
; #pragma unroll
;             for (int bt = 0; bt < 2; ++bt) {
;                 if (bt == 1) { ATT_VLOAD16(1, 0); asm volatile("" ::: "memory"); }
; #pragma unroll
;                 for (int pp = 0; pp < 4; ++pp)
; #pragma unroll
;                     for (int mt = 0; mt < 4; ++mt) o[mt] = mfma16(vb2[0][pp * 4 + mt], pb[bt * 4 + pp], o[mt]);
	v_mfma_f32_16x16x32_bf16 v[218:221], v[218:221], v[108:111], 0
	s_waitcnt lgkmcnt(2)
	v_mfma_f32_16x16x32_bf16 v[222:225], v[222:225], v[108:111], 0
	s_waitcnt lgkmcnt(1)
	v_mfma_f32_16x16x32_bf16 v[226:229], v[226:229], v[108:111], 0
	s_waitcnt lgkmcnt(0)
	v_mfma_f32_16x16x32_bf16 v[108:111], v[230:233], v[108:111], 0
	ds_read_b128 v[230:233], v169 offset:36928
	s_waitcnt lgkmcnt(0)
	v_mfma_f32_16x16x32_bf16 v[218:221], v[230:233], v[48:51], v[218:221]
	ds_read_b128 v[230:233], v169 offset:45376
	s_waitcnt lgkmcnt(0)
	v_mfma_f32_16x16x32_bf16 v[222:225], v[230:233], v[48:51], v[222:225]
	ds_read_b128 v[230:233], v169 offset:53824
	s_waitcnt lgkmcnt(0)
	v_mfma_f32_16x16x32_bf16 v[226:229], v[230:233], v[48:51], v[226:229]
	ds_read_b128 v[230:233], v170 offset:36928
	s_waitcnt lgkmcnt(0)
	v_mfma_f32_16x16x32_bf16 v[48:51], v[230:233], v[48:51], v[108:111]
	s_nop 2
	ds_read_b128 v[108:111], v169 offset:36992
	s_waitcnt lgkmcnt(0)
	v_mfma_f32_16x16x32_bf16 v[108:111], v[108:111], v[36:39], v[218:221]
	s_nop 2
	ds_read_b128 v[218:221], v169 offset:45440
	s_waitcnt lgkmcnt(0)
	v_mfma_f32_16x16x32_bf16 v[218:221], v[218:221], v[36:39], v[222:225]
	s_nop 2
	ds_read_b128 v[222:225], v169 offset:53888
	s_waitcnt lgkmcnt(0)
	v_mfma_f32_16x16x32_bf16 v[222:225], v[222:225], v[36:39], v[226:229]
	s_nop 2
	ds_read_b128 v[226:229], v170 offset:36992
	s_waitcnt lgkmcnt(0)
	v_mfma_f32_16x16x32_bf16 v[36:39], v[226:229], v[36:39], v[48:51]
	s_nop 2
	ds_read_b128 v[48:51], v169 offset:37056
	s_waitcnt lgkmcnt(0)
	v_mfma_f32_16x16x32_bf16 v[48:51], v[48:51], v[32:35], v[108:111]
	s_nop 2
	ds_read_b128 v[108:111], v169 offset:45504
	s_waitcnt lgkmcnt(0)
	v_mfma_f32_16x16x32_bf16 v[108:111], v[108:111], v[32:35], v[218:221]
	s_nop 2
	ds_read_b128 v[218:221], v169 offset:53952
	s_waitcnt lgkmcnt(0)
	v_mfma_f32_16x16x32_bf16 v[218:221], v[218:221], v[32:35], v[222:225]
	s_nop 2
	ds_read_b128 v[222:225], v170 offset:37056
	s_waitcnt lgkmcnt(0)
	v_mfma_f32_16x16x32_bf16 v[32:35], v[222:225], v[32:35], v[36:39]
	s_nop 2
	ds_read_b128 v[36:39], v169 offset:37120
	s_waitcnt lgkmcnt(0)
	v_mfma_f32_16x16x32_bf16 v[36:39], v[36:39], v[28:31], v[48:51]
	s_nop 2
	ds_read_b128 v[48:51], v169 offset:45568
	s_waitcnt lgkmcnt(0)
	v_mfma_f32_16x16x32_bf16 v[48:51], v[48:51], v[28:31], v[108:111]
	s_nop 2
	ds_read_b128 v[108:111], v169 offset:54016
	s_waitcnt lgkmcnt(0)
	v_mfma_f32_16x16x32_bf16 v[108:111], v[108:111], v[28:31], v[218:221]
	s_nop 2
	ds_read_b128 v[218:221], v170 offset:37120
	s_waitcnt lgkmcnt(0)
	v_mfma_f32_16x16x32_bf16 v[28:31], v[218:221], v[28:31], v[32:35]
	s_nop 2
	ds_read_b128 v[32:35], v169 offset:37184
	s_waitcnt lgkmcnt(0)
	v_mfma_f32_16x16x32_bf16 v[32:35], v[32:35], v[24:27], v[36:39]
	s_nop 2
	ds_read_b128 v[36:39], v169 offset:45632
	s_waitcnt lgkmcnt(0)
	v_mfma_f32_16x16x32_bf16 v[36:39], v[36:39], v[24:27], v[48:51]
	s_nop 2
	ds_read_b128 v[48:51], v169 offset:54080
	s_waitcnt lgkmcnt(0)
	v_mfma_f32_16x16x32_bf16 v[48:51], v[48:51], v[24:27], v[108:111]
	s_nop 2
	ds_read_b128 v[108:111], v170 offset:37184
	s_waitcnt lgkmcnt(0)
	v_mfma_f32_16x16x32_bf16 v[24:27], v[108:111], v[24:27], v[28:31]
	s_nop 2
	ds_read_b128 v[28:31], v169 offset:37248
	v_cvt_pk_bf16_f32 v108, v184, v185
	v_cvt_pk_bf16_f32 v109, v186, v187
	s_waitcnt lgkmcnt(0)
	v_mfma_f32_16x16x32_bf16 v[28:31], v[28:31], v[20:23], v[32:35]
	s_nop 2
	ds_read_b128 v[32:35], v169 offset:45696
	v_cvt_pk_bf16_f32 v110, v188, v189
	v_cvt_pk_bf16_f32 v111, v190, v191
	s_waitcnt lgkmcnt(0)
	v_mfma_f32_16x16x32_bf16 v[32:35], v[32:35], v[20:23], v[36:39]
	s_nop 2
	ds_read_b128 v[36:39], v169 offset:54144
	s_waitcnt lgkmcnt(0)
	v_mfma_f32_16x16x32_bf16 v[36:39], v[36:39], v[20:23], v[48:51]
	s_nop 2
	ds_read_b128 v[48:51], v170 offset:37248
	s_waitcnt lgkmcnt(0)
	v_mfma_f32_16x16x32_bf16 v[20:23], v[48:51], v[20:23], v[24:27]
	s_nop 2
	ds_read_b128 v[24:27], v169 offset:37312
	v_cvt_pk_bf16_f32 v48, v192, v193
	v_cvt_pk_bf16_f32 v49, v194, v195
	s_waitcnt lgkmcnt(0)
	v_mfma_f32_16x16x32_bf16 v[24:27], v[24:27], v[16:19], v[28:31]
	s_nop 2
	ds_read_b128 v[28:31], v169 offset:45760
	v_cvt_pk_bf16_f32 v50, v196, v197
	v_cvt_pk_bf16_f32 v51, v198, v199
	s_waitcnt lgkmcnt(0)
	v_mfma_f32_16x16x32_bf16 v[28:31], v[28:31], v[16:19], v[32:35]
	s_nop 2
	ds_read_b128 v[32:35], v169 offset:54208
	s_waitcnt lgkmcnt(0)
	v_mfma_f32_16x16x32_bf16 v[32:35], v[32:35], v[16:19], v[36:39]
	s_nop 2
	ds_read_b128 v[36:39], v170 offset:37312
	s_waitcnt lgkmcnt(0)
	v_mfma_f32_16x16x32_bf16 v[16:19], v[36:39], v[16:19], v[20:23]
	s_nop 2
	v_cvt_pk_bf16_f32 v20, v200, v201
	v_cvt_pk_bf16_f32 v21, v202, v203
	v_cvt_pk_bf16_f32 v22, v204, v205
	s_waitcnt vmcnt(15)
	v_mfma_f32_16x16x32_bf16 v[24:27], v[40:43], v[108:111], v[24:27]
	v_cvt_pk_bf16_f32 v23, v206, v207
	v_cvt_pk_bf16_f32 v36, v208, v209
	v_cvt_pk_bf16_f32 v37, v210, v211
	s_waitcnt vmcnt(14)
	v_mfma_f32_16x16x32_bf16 v[28:31], v[44:47], v[108:111], v[28:31]
	v_cvt_pk_bf16_f32 v38, v212, v213
	v_cvt_pk_bf16_f32 v39, v214, v215
	s_waitcnt vmcnt(13)
	v_mfma_f32_16x16x32_bf16 v[32:35], v[52:55], v[108:111], v[32:35]
	s_waitcnt vmcnt(12)
	v_mfma_f32_16x16x32_bf16 v[16:19], v[56:59], v[108:111], v[16:19]
	s_waitcnt vmcnt(11)
	v_mfma_f32_16x16x32_bf16 v[24:27], v[60:63], v[48:51], v[24:27]
	s_waitcnt vmcnt(10)
	v_mfma_f32_16x16x32_bf16 v[28:31], v[64:67], v[48:51], v[28:31]
	s_waitcnt vmcnt(9)
	v_mfma_f32_16x16x32_bf16 v[32:35], v[68:71], v[48:51], v[32:35]
	s_waitcnt vmcnt(8)
	v_mfma_f32_16x16x32_bf16 v[16:19], v[72:75], v[48:51], v[16:19]
	s_waitcnt vmcnt(7)
	v_mfma_f32_16x16x32_bf16 v[24:27], v[76:79], v[20:23], v[24:27]
	s_waitcnt vmcnt(6)
; __device__ __forceinline__ unsigned pk2(float lo, float hi) { const f32x2 v = {lo, hi}; const bf16x2_t b = __builtin_convertvector(v, bf16x2_t); return __builtin_bit_cast(unsigned, b); }
; __device__ __forceinline__ float silu_f(float v) { return v * __builtin_amdgcn_rcpf(1.f + __expf(-v)); }
; __device__ __forceinline__ f32x4 mfma16(bf16x8 a, bf16x8 b, f32x4 c) { return __builtin_amdgcn_mfma_f32_16x16x32_bf16(a, b, c, 0, 0, 0); }
; #define ATT_VLOAD16(bt, dstb) do { _Pragma("unroll") for (int pp_ = 0; pp_ < 4; ++pp_) { \
;                 const size_t tokb_ = (size_t)b * 16384 + (rs + (bt) * 4 + pp_) * 64 + kc0 + 8 * g; \
;                 _Pragma("unroll") for (int mt_ = 0; mt_ < 4; ++mt_) vb2[dstb][pp_ * 4 + mt_] = *(const bf16x8*)(AVT + (size_t)(h * 64 + mt_ * 16 + q16) * MR + tokb_); } } while (0)
; __device__ __forceinline__ void phase_attn(const Args& a, unsigned char* smem, int tid, int lane, int wave, bf16_t* Yout) {
;     ...
;                 if (bt == 1) { ATT_VLOAD16(1, 0); asm volatile("" ::: "memory"); }
; #pragma unroll
;                 for (int pp = 0; pp < 4; ++pp)
; #pragma unroll
;                     for (int mt = 0; mt < 4; ++mt) o[mt] = mfma16(vb2[0][pp * 4 + mt], pb[bt * 4 + pp], o[mt]);
;             }
;     ...
;             const float inv = 1.f / l;
; #pragma unroll
;             for (int mt = 0; mt < 4; ++mt) {
;                 const size_t off = qrow * 1024 + h * 64 + mt * 16 + 4 * g;
;                 const u32x2 z = *(const u32x2*)(AZ + off);
;                 u32x2 w; w.x = pk2(o[mt][0] * inv * silu_f(bflo(z.x)), o[mt][1] * inv * silu_f(bfhi(z.x)));
;                 w.y = pk2(o[mt][2] * inv * silu_f(bflo(z.y)), o[mt][3] * inv * silu_f(bfhi(z.y)));
;                 *(u32x2*)(Yout + off) = w;
	v_mfma_f32_16x16x32_bf16 v[40:43], v[80:83], v[20:23], v[28:31]
	s_waitcnt vmcnt(5)
	v_mfma_f32_16x16x32_bf16 v[32:35], v[84:87], v[20:23], v[32:35]
	s_waitcnt vmcnt(4)
	v_mfma_f32_16x16x32_bf16 v[16:19], v[88:91], v[20:23], v[16:19]
	s_waitcnt vmcnt(3)
	v_mfma_f32_16x16x32_bf16 v[28:31], v[92:95], v[36:39], v[24:27]
	s_waitcnt vmcnt(2)
	v_mfma_f32_16x16x32_bf16 v[24:27], v[96:99], v[36:39], v[40:43]
	s_waitcnt vmcnt(1)
	v_mfma_f32_16x16x32_bf16 v[20:23], v[100:103], v[36:39], v[32:35]
	s_waitcnt vmcnt(0)
	v_mfma_f32_16x16x32_bf16 v[16:19], v[104:107], v[36:39], v[16:19]
	s_nop 0
	global_load_dwordx4 v[32:35], v[154:155], off offset:512
	global_load_dwordx4 v[36:39], v[152:153], off offset:512
	global_load_dwordx4 v[40:43], v[150:151], off offset:512
	global_load_dwordx4 v[44:47], v[148:149], off offset:512
	global_load_dwordx4 v[48:51], v[154:155], off offset:640
	global_load_dwordx4 v[52:55], v[152:153], off offset:640
	global_load_dwordx4 v[56:59], v[150:151], off offset:640
	global_load_dwordx4 v[60:63], v[148:149], off offset:640
	global_load_dwordx4 v[64:67], v[154:155], off offset:768
	global_load_dwordx4 v[68:71], v[152:153], off offset:768
	global_load_dwordx4 v[72:75], v[150:151], off offset:768
	global_load_dwordx4 v[76:79], v[148:149], off offset:768
	global_load_dwordx4 v[80:83], v[154:155], off offset:896
	global_load_dwordx4 v[84:87], v[152:153], off offset:896
	global_load_dwordx4 v[88:91], v[150:151], off offset:896
	global_load_dwordx4 v[92:95], v[148:149], off offset:896
	s_mov_b32 vcc_lo, s51
	s_mov_b32 vcc_hi, 0
	v_lshl_add_u64 v[248:249], v[136:137], 0, vcc
	v_lshl_add_u64 v[240:241], v[248:249], 0, v[144:145]
	v_lshl_add_u64 v[242:243], v[248:249], 0, v[142:143]
	v_lshl_add_u64 v[244:245], v[248:249], 0, v[140:141]
	v_lshl_add_u64 v[246:247], v[248:249], 0, v[138:139]
	global_load_dwordx2 v[232:233], v[240:241], off
	global_load_dwordx2 v[234:235], v[242:243], off
	global_load_dwordx2 v[236:237], v[244:245], off
	global_load_dwordx2 v[238:239], v[246:247], off
	s_waitcnt vmcnt(19)
	v_mfma_f32_16x16x32_bf16 v[28:31], v[32:35], v[12:15], v[28:31]
	s_waitcnt vmcnt(18)
	v_mfma_f32_16x16x32_bf16 v[24:27], v[36:39], v[12:15], v[24:27]
	s_waitcnt vmcnt(17)
	v_mfma_f32_16x16x32_bf16 v[20:23], v[40:43], v[12:15], v[20:23]
	s_waitcnt vmcnt(16)
	v_mfma_f32_16x16x32_bf16 v[12:15], v[44:47], v[12:15], v[16:19]
	s_waitcnt vmcnt(15)
	v_mfma_f32_16x16x32_bf16 v[16:19], v[48:51], v[8:11], v[28:31]
	s_waitcnt vmcnt(14)
	v_mfma_f32_16x16x32_bf16 v[24:27], v[52:55], v[8:11], v[24:27]
	s_waitcnt vmcnt(13)
	v_mfma_f32_16x16x32_bf16 v[20:23], v[56:59], v[8:11], v[20:23]
	s_waitcnt vmcnt(12)
	v_mfma_f32_16x16x32_bf16 v[8:11], v[60:63], v[8:11], v[12:15]
	s_waitcnt vmcnt(11)
	v_mfma_f32_16x16x32_bf16 v[12:15], v[64:67], v[4:7], v[16:19]
	s_waitcnt vmcnt(7)
	v_mfma_f32_16x16x32_bf16 v[28:31], v[80:83], v[0:3], v[12:15]
	v_mfma_f32_16x16x32_bf16 v[16:19], v[68:71], v[4:7], v[24:27]
	s_nop 4
	v_add_f32_e32 v12, v216, v217
	v_div_scale_f32 v13, s[6:7], v12, v12, 1.0
	v_rcp_f32_e32 v14, v13
	v_mfma_f32_16x16x32_bf16 v[24:27], v[76:79], v[4:7], v[8:11]
	v_fma_f32 v15, -v13, v14, 1.0
	v_fmac_f32_e32 v14, v15, v14
	v_div_scale_f32 v15, vcc, 1.0, v12, 1.0
	s_waitcnt vmcnt(6)
	v_mfma_f32_16x16x32_bf16 v[8:11], v[84:87], v[0:3], v[16:19]
	s_nop 2
	v_mul_f32_e32 v16, v15, v14
	v_fma_f32 v17, -v13, v16, v15
	v_fmac_f32_e32 v16, v17, v14
	v_fma_f32 v13, -v13, v16, v15
	v_div_fmas_f32 v13, v13, v14, v16
	v_lshl_add_u64 v[14:15], v[136:137], 0, v[144:145]
	v_add_co_u32_e32 v16, vcc, s51, v14
	v_div_fixup_f32 v12, v13, v12, 1.0
	s_nop 0
	v_addc_co_u32_e32 v17, vcc, 0, v15, vcc
	s_nop 0
	v_mfma_f32_16x16x32_bf16 v[20:23], v[72:75], v[4:7], v[20:23]
	v_add_co_u32_e32 v14, vcc, s46, v14
	s_waitcnt vmcnt(3)
	v_mov_b32_e32 v16, v232
	v_mov_b32_e32 v17, v233
	v_lshlrev_b32_e32 v18, 16, v16
	v_mul_f32_e32 v13, 0xbfb8aa3b, v18
	v_exp_f32_e32 v13, v13
	v_and_b32_e32 v19, 0xffff0000, v16
	v_mfma_f32_16x16x32_bf16 v[4:7], v[88:91], v[0:3], v[20:23]
	v_addc_co_u32_e32 v15, vcc, 0, v15, vcc
	v_add_f32_e32 v13, 1.0, v13
	s_nop 0
	v_rcp_f32_e32 v20, v13
	v_pk_mul_f32 v[22:23], v[28:29], v[12:13] op_sel_hi:[1,0]
	v_mul_f32_e32 v13, 0xbfb8aa3b, v19
	v_exp_f32_e32 v13, v13
	v_mfma_f32_16x16x32_bf16 v[0:3], v[92:95], v[0:3], v[24:27]
	v_add_f32_e32 v13, 1.0, v13
	v_rcp_f32_e32 v21, v13
	s_nop 0
	v_pk_mul_f32 v[18:19], v[20:21], v[18:19]
	s_nop 0
	v_pk_mul_f32 v[18:19], v[22:23], v[18:19]
	s_nop 0
	v_cvt_pk_bf16_f32 v16, v18, v19
	v_lshlrev_b32_e32 v18, 16, v17
	v_mul_f32_e32 v13, 0xbfb8aa3b, v18
	v_exp_f32_e32 v13, v13
	v_and_b32_e32 v19, 0xffff0000, v17
	v_add_f32_e32 v13, 1.0, v13
	v_rcp_f32_e32 v20, v13
	v_pk_mul_f32 v[22:23], v[30:31], v[12:13] op_sel_hi:[1,0]
	v_mul_f32_e32 v13, 0xbfb8aa3b, v19
	v_exp_f32_e32 v13, v13
	s_nop 0
	v_add_f32_e32 v13, 1.0, v13
	v_rcp_f32_e32 v21, v13
	s_nop 0
	v_pk_mul_f32 v[18:19], v[20:21], v[18:19]
	s_nop 0
	v_pk_mul_f32 v[18:19], v[22:23], v[18:19]
	s_nop 0
	v_cvt_pk_bf16_f32 v17, v18, v19
	global_store_dwordx2 v[14:15], v[16:17], off
	v_lshl_add_u64 v[14:15], v[136:137], 0, v[142:143]
	v_add_co_u32_e32 v16, vcc, s51, v14
	s_nop 1
	v_addc_co_u32_e32 v17, vcc, 0, v15, vcc
	s_nop 0
	s_waitcnt vmcnt(3)
; __device__ __forceinline__ unsigned pk2(float lo, float hi) { const f32x2 v = {lo, hi}; const bf16x2_t b = __builtin_convertvector(v, bf16x2_t); return __builtin_bit_cast(unsigned, b); }
; __device__ __forceinline__ float silu_f(float v) { return v * __builtin_amdgcn_rcpf(1.f + __expf(-v)); }
; __device__ __forceinline__ void phase_attn(const Args& a, unsigned char* smem, int tid, int lane, int wave, bf16_t* Yout) {
;     ...
;             const float inv = 1.f / l;
; #pragma unroll
;             for (int mt = 0; mt < 4; ++mt) {
;                 const size_t off = qrow * 1024 + h * 64 + mt * 16 + 4 * g;
;                 const u32x2 z = *(const u32x2*)(AZ + off);
;                 u32x2 w; w.x = pk2(o[mt][0] * inv * silu_f(bflo(z.x)), o[mt][1] * inv * silu_f(bfhi(z.x)));
;                 w.y = pk2(o[mt][2] * inv * silu_f(bflo(z.y)), o[mt][3] * inv * silu_f(bfhi(z.y)));
;                 *(u32x2*)(Yout + off) = w;
	v_mov_b32_e32 v16, v234
	v_mov_b32_e32 v17, v235
	v_lshlrev_b32_e32 v18, 16, v16
	v_mul_f32_e32 v13, 0xbfb8aa3b, v18
	v_exp_f32_e32 v13, v13
	v_and_b32_e32 v19, 0xffff0000, v16
	v_lshlrev_b32_e32 v16, 16, v17
	v_and_b32_e32 v17, 0xffff0000, v17
	v_add_f32_e32 v13, 1.0, v13
	v_rcp_f32_e32 v20, v13
	v_pk_mul_f32 v[8:9], v[8:9], v[12:13] op_sel_hi:[1,0]
	v_mul_f32_e32 v13, 0xbfb8aa3b, v19
	v_exp_f32_e32 v13, v13
	s_nop 0
	v_add_f32_e32 v13, 1.0, v13
	v_rcp_f32_e32 v21, v13
	v_pk_mul_f32 v[10:11], v[10:11], v[12:13] op_sel_hi:[1,0]
	v_pk_mul_f32 v[4:5], v[4:5], v[12:13] op_sel_hi:[1,0]
	v_pk_mul_f32 v[6:7], v[6:7], v[12:13] op_sel_hi:[1,0]
	v_pk_mul_f32 v[18:19], v[20:21], v[18:19]
	v_pk_mul_f32 v[0:1], v[0:1], v[12:13] op_sel_hi:[1,0]
	v_pk_mul_f32 v[8:9], v[8:9], v[18:19]
	v_pk_mul_f32 v[2:3], v[2:3], v[12:13] op_sel_hi:[1,0]
	v_cvt_pk_bf16_f32 v8, v8, v9
	v_mul_f32_e32 v9, 0xbfb8aa3b, v16
	v_exp_f32_e32 v9, v9
	s_nop 0
	v_add_f32_e32 v9, 1.0, v9
	v_rcp_f32_e32 v18, v9
	v_mul_f32_e32 v9, 0xbfb8aa3b, v17
	v_exp_f32_e32 v9, v9
	s_nop 0
	v_add_f32_e32 v9, 1.0, v9
	v_rcp_f32_e32 v19, v9
	s_nop 0
	v_pk_mul_f32 v[16:17], v[18:19], v[16:17]
	s_nop 0
	v_pk_mul_f32 v[10:11], v[10:11], v[16:17]
	s_nop 0
	v_cvt_pk_bf16_f32 v9, v10, v11
	v_add_co_u32_e32 v10, vcc, s46, v14
	s_nop 1
	v_addc_co_u32_e32 v11, vcc, 0, v15, vcc
	global_store_dwordx2 v[10:11], v[8:9], off
	v_lshl_add_u64 v[8:9], v[136:137], 0, v[140:141]
	v_add_co_u32_e32 v10, vcc, s51, v8
	s_nop 1
	v_addc_co_u32_e32 v11, vcc, 0, v9, vcc
	s_nop 0
	s_waitcnt vmcnt(3)
	v_mov_b32_e32 v10, v236
	v_mov_b32_e32 v11, v237
	v_lshlrev_b32_e32 v14, 16, v10
	v_and_b32_e32 v15, 0xffff0000, v10
	v_mul_f32_e32 v10, 0xbfb8aa3b, v14
	v_exp_f32_e32 v10, v10
	s_nop 0
	v_add_f32_e32 v10, 1.0, v10
	v_rcp_f32_e32 v16, v10
	v_mul_f32_e32 v10, 0xbfb8aa3b, v15
	v_exp_f32_e32 v10, v10
	s_nop 0
	v_add_f32_e32 v10, 1.0, v10
	v_rcp_f32_e32 v17, v10
	v_lshlrev_b32_e32 v10, 16, v11
	v_and_b32_e32 v11, 0xffff0000, v11
	v_pk_mul_f32 v[14:15], v[16:17], v[14:15]
	s_nop 0
	v_pk_mul_f32 v[4:5], v[4:5], v[14:15]
	s_nop 0
	v_cvt_pk_bf16_f32 v4, v4, v5
	v_mul_f32_e32 v5, 0xbfb8aa3b, v10
	v_exp_f32_e32 v5, v5
	s_nop 0
	v_add_f32_e32 v5, 1.0, v5
	v_rcp_f32_e32 v14, v5
	v_mul_f32_e32 v5, 0xbfb8aa3b, v11
	v_exp_f32_e32 v5, v5
	s_nop 0
	v_add_f32_e32 v5, 1.0, v5
	v_rcp_f32_e32 v15, v5
	s_nop 0
	v_pk_mul_f32 v[10:11], v[14:15], v[10:11]
	s_nop 0
	v_pk_mul_f32 v[6:7], v[6:7], v[10:11]
	s_nop 0
	v_cvt_pk_bf16_f32 v5, v6, v7
	v_add_co_u32_e32 v6, vcc, s46, v8
	s_nop 1
	v_addc_co_u32_e32 v7, vcc, 0, v9, vcc
	global_store_dwordx2 v[6:7], v[4:5], off
	v_lshl_add_u64 v[4:5], v[136:137], 0, v[138:139]
	v_add_co_u32_e32 v6, vcc, s51, v4
	v_lshl_add_u64 v[136:137], v[136:137], 0, s[20:21]
	s_nop 0
	v_addc_co_u32_e32 v7, vcc, 0, v5, vcc
	s_nop 0
	s_waitcnt vmcnt(3)
	v_mov_b32_e32 v6, v238
	v_mov_b32_e32 v7, v239
	v_lshlrev_b32_e32 v8, 16, v6
	v_and_b32_e32 v9, 0xffff0000, v6
	v_mul_f32_e32 v6, 0xbfb8aa3b, v8
	v_exp_f32_e32 v6, v6
	s_nop 0
	v_add_f32_e32 v6, 1.0, v6
	v_rcp_f32_e32 v10, v6
	v_mul_f32_e32 v6, 0xbfb8aa3b, v9
	v_exp_f32_e32 v6, v6
	s_nop 0
	v_add_f32_e32 v6, 1.0, v6
	v_rcp_f32_e32 v11, v6
	v_lshlrev_b32_e32 v6, 16, v7
	v_and_b32_e32 v7, 0xffff0000, v7
	v_pk_mul_f32 v[8:9], v[10:11], v[8:9]
	s_nop 0
	v_pk_mul_f32 v[0:1], v[0:1], v[8:9]
	s_nop 0
	v_cvt_pk_bf16_f32 v0, v0, v1
	v_mul_f32_e32 v1, 0xbfb8aa3b, v6
	v_exp_f32_e32 v1, v1
	s_nop 0
	v_add_f32_e32 v1, 1.0, v1
	v_rcp_f32_e32 v8, v1
	v_mul_f32_e32 v1, 0xbfb8aa3b, v7
	v_exp_f32_e32 v1, v1
	s_nop 0
	v_add_f32_e32 v1, 1.0, v1
	v_rcp_f32_e32 v9, v1
	s_nop 0
	v_pk_mul_f32 v[6:7], v[8:9], v[6:7]
	s_nop 0
	v_pk_mul_f32 v[2:3], v[2:3], v[6:7]
	s_nop 0
	v_cvt_pk_bf16_f32 v1, v2, v3
	v_add_co_u32_e32 v2, vcc, 0x100000, v4
	s_nop 1
	v_addc_co_u32_e32 v3, vcc, 0, v5, vcc
	global_store_dwordx2 v[2:3], v[0:1], off
	s_cbranch_scc1 .LBB0_329
